# v5 + 60 bytes of s_nop after the new preamble so that every later code address keeps its v2 offset modulo 4096 (code placement control)
# speedup vs baseline: 1.0070x; 1.0070x over previous
; __device__ __forceinline__ void p0_modvec(const Params& p, LAS unsigned char* lds, int tid, int lane, int wave) {
;     ...
;     for (int i = tid; i < 9 * 2048; i += 512) { const float v = i < 8 * 2048 ? c[i] : cc[i - 8 * 2048]; svT[(i & 2047) * 12 + (i >> 11)] = v / (1.0f + __expf(-v)); }
.LBB0_12:
	v_lshlrev_b32_e32 v6, 2, v0
	v_mul_u32_u24_e32 v7, 48, v0
	v_add_u32_e32 v8, 0x12000, v7
	global_load_dword v16, v6, s[14:15]
	global_load_dword v17, v6, s[14:15] offset:2048
	s_add_u32 s6, s14, 0x1000
	s_addc_u32 s7, s15, 0
	global_load_dword v18, v6, s[6:7]
	global_load_dword v19, v6, s[6:7] offset:2048
	s_add_u32 s6, s14, 0x2000
	s_addc_u32 s7, s15, 0
	global_load_dword v20, v6, s[6:7]
	global_load_dword v21, v6, s[6:7] offset:2048
	s_add_u32 s6, s14, 0x3000
	s_addc_u32 s7, s15, 0
	global_load_dword v22, v6, s[6:7]
	global_load_dword v23, v6, s[6:7] offset:2048
	s_add_u32 s6, s14, 0x4000
	s_addc_u32 s7, s15, 0
	global_load_dword v24, v6, s[6:7]
	global_load_dword v25, v6, s[6:7] offset:2048
	s_add_u32 s6, s14, 0x5000
	s_addc_u32 s7, s15, 0
	global_load_dword v26, v6, s[6:7]
	global_load_dword v27, v6, s[6:7] offset:2048
	s_add_u32 s6, s14, 0x6000
	s_addc_u32 s7, s15, 0
	global_load_dword v28, v6, s[6:7]
	global_load_dword v29, v6, s[6:7] offset:2048
	s_add_u32 s6, s14, 0x7000
	s_addc_u32 s7, s15, 0
	global_load_dword v30, v6, s[6:7]
	global_load_dword v31, v6, s[6:7] offset:2048
	s_add_u32 s6, s14, 0x8000
	s_addc_u32 s7, s15, 0
	global_load_dword v32, v6, s[6:7]
	global_load_dword v33, v6, s[6:7] offset:2048
	s_add_u32 s6, s14, 0x9000
	s_addc_u32 s7, s15, 0
	global_load_dword v34, v6, s[6:7]
	global_load_dword v35, v6, s[6:7] offset:2048
	s_add_u32 s6, s14, 0xa000
	s_addc_u32 s7, s15, 0
	global_load_dword v36, v6, s[6:7]
	global_load_dword v37, v6, s[6:7] offset:2048
	s_add_u32 s6, s14, 0xb000
	s_addc_u32 s7, s15, 0
	global_load_dword v38, v6, s[6:7]
	global_load_dword v39, v6, s[6:7] offset:2048
	s_add_u32 s6, s14, 0xc000
	s_addc_u32 s7, s15, 0
	global_load_dword v40, v6, s[6:7]
	global_load_dword v41, v6, s[6:7] offset:2048
	s_add_u32 s6, s14, 0xd000
	s_addc_u32 s7, s15, 0
	global_load_dword v42, v6, s[6:7]
	global_load_dword v43, v6, s[6:7] offset:2048
	s_add_u32 s6, s14, 0xe000
	s_addc_u32 s7, s15, 0
	global_load_dword v44, v6, s[6:7]
	global_load_dword v45, v6, s[6:7] offset:2048
	s_add_u32 s6, s14, 0xf000
	s_addc_u32 s7, s15, 0
	global_load_dword v46, v6, s[6:7]
	global_load_dword v47, v6, s[6:7] offset:2048
	global_load_dword v48, v6, s[18:19]
	global_load_dword v49, v6, s[18:19] offset:2048
	s_add_u32 s6, s18, 0x1000
	s_addc_u32 s7, s19, 0
	global_load_dword v50, v6, s[6:7]
	global_load_dword v51, v6, s[6:7] offset:2048
	s_waitcnt vmcnt(35)
	v_mul_f32_e32 v10, 0xbfb8aa3b, v16
	v_exp_f32_e32 v10, v10
	s_nop 0
	v_add_f32_e32 v9, 1.0, v10
	v_div_scale_f32 v10, s[12:13], v9, v9, v16
	v_rcp_f32_e32 v11, v10
	v_div_scale_f32 v12, vcc, v16, v9, v16
	v_fma_f32 v13, -v10, v11, 1.0
	v_fmac_f32_e32 v11, v13, v11
	v_mul_f32_e32 v13, v12, v11
	v_fma_f32 v14, -v10, v13, v12
	v_fmac_f32_e32 v13, v14, v11
	v_fma_f32 v10, -v10, v13, v12
	v_div_fmas_f32 v10, v10, v11, v13
	v_div_fixup_f32 v16, v10, v9, v16
	ds_write_b32 v7, v16 offset:0
	s_waitcnt vmcnt(34)
	v_mul_f32_e32 v10, 0xbfb8aa3b, v17
	v_exp_f32_e32 v10, v10
	s_nop 0
	v_add_f32_e32 v9, 1.0, v10
	v_div_scale_f32 v10, s[12:13], v9, v9, v17
	v_rcp_f32_e32 v11, v10
	v_div_scale_f32 v12, vcc, v17, v9, v17
	v_fma_f32 v13, -v10, v11, 1.0
	v_fmac_f32_e32 v11, v13, v11
	v_mul_f32_e32 v13, v12, v11
	v_fma_f32 v14, -v10, v13, v12
	v_fmac_f32_e32 v13, v14, v11
	v_fma_f32 v10, -v10, v13, v12
	v_div_fmas_f32 v10, v10, v11, v13
	v_div_fixup_f32 v17, v10, v9, v17
	ds_write_b32 v7, v17 offset:24576
	s_waitcnt vmcnt(33)
	v_mul_f32_e32 v10, 0xbfb8aa3b, v18
	v_exp_f32_e32 v10, v10
	s_nop 0
	v_add_f32_e32 v9, 1.0, v10
	v_div_scale_f32 v10, s[12:13], v9, v9, v18
	v_rcp_f32_e32 v11, v10
	v_div_scale_f32 v12, vcc, v18, v9, v18
	v_fma_f32 v13, -v10, v11, 1.0
	v_fmac_f32_e32 v11, v13, v11
	v_mul_f32_e32 v13, v12, v11
	v_fma_f32 v14, -v10, v13, v12
	v_fmac_f32_e32 v13, v14, v11
	v_fma_f32 v10, -v10, v13, v12
	v_div_fmas_f32 v10, v10, v11, v13
	v_div_fixup_f32 v18, v10, v9, v18
	ds_write_b32 v7, v18 offset:49152
	s_waitcnt vmcnt(32)
	v_mul_f32_e32 v10, 0xbfb8aa3b, v19
	v_exp_f32_e32 v10, v10
	s_nop 0
	v_add_f32_e32 v9, 1.0, v10
	v_div_scale_f32 v10, s[12:13], v9, v9, v19
	v_rcp_f32_e32 v11, v10
	v_div_scale_f32 v12, vcc, v19, v9, v19
	v_fma_f32 v13, -v10, v11, 1.0
	v_fmac_f32_e32 v11, v13, v11
	v_mul_f32_e32 v13, v12, v11
	v_fma_f32 v14, -v10, v13, v12
	v_fmac_f32_e32 v13, v14, v11
	v_fma_f32 v10, -v10, v13, v12
	v_div_fmas_f32 v10, v10, v11, v13
	v_div_fixup_f32 v19, v10, v9, v19
	ds_write_b32 v8, v19 offset:0
	s_waitcnt vmcnt(31)
	v_mul_f32_e32 v10, 0xbfb8aa3b, v20
	v_exp_f32_e32 v10, v10
	s_nop 0
	v_add_f32_e32 v9, 1.0, v10
	v_div_scale_f32 v10, s[12:13], v9, v9, v20
	v_rcp_f32_e32 v11, v10
	v_div_scale_f32 v12, vcc, v20, v9, v20
	v_fma_f32 v13, -v10, v11, 1.0
	v_fmac_f32_e32 v11, v13, v11
	v_mul_f32_e32 v13, v12, v11
	v_fma_f32 v14, -v10, v13, v12
	v_fmac_f32_e32 v13, v14, v11
	v_fma_f32 v10, -v10, v13, v12
	v_div_fmas_f32 v10, v10, v11, v13
	v_div_fixup_f32 v20, v10, v9, v20
	ds_write_b32 v7, v20 offset:4
	s_waitcnt vmcnt(30)
	v_mul_f32_e32 v10, 0xbfb8aa3b, v21
	v_exp_f32_e32 v10, v10
	s_nop 0
	v_add_f32_e32 v9, 1.0, v10
	v_div_scale_f32 v10, s[12:13], v9, v9, v21
	v_rcp_f32_e32 v11, v10
	v_div_scale_f32 v12, vcc, v21, v9, v21
	v_fma_f32 v13, -v10, v11, 1.0
	v_fmac_f32_e32 v11, v13, v11
	v_mul_f32_e32 v13, v12, v11
	v_fma_f32 v14, -v10, v13, v12
	v_fmac_f32_e32 v13, v14, v11
	v_fma_f32 v10, -v10, v13, v12
	v_div_fmas_f32 v10, v10, v11, v13
	v_div_fixup_f32 v21, v10, v9, v21
	ds_write_b32 v7, v21 offset:24580
	s_waitcnt vmcnt(29)
; __device__ __forceinline__ void p0_modvec(const Params& p, LAS unsigned char* lds, int tid, int lane, int wave) {
;     ...
;     for (int i = tid; i < 9 * 2048; i += 512) { const float v = i < 8 * 2048 ? c[i] : cc[i - 8 * 2048]; svT[(i & 2047) * 12 + (i >> 11)] = v / (1.0f + __expf(-v)); }
	v_mul_f32_e32 v10, 0xbfb8aa3b, v22
	v_exp_f32_e32 v10, v10
	s_nop 0
	v_add_f32_e32 v9, 1.0, v10
	v_div_scale_f32 v10, s[12:13], v9, v9, v22
	v_rcp_f32_e32 v11, v10
	v_div_scale_f32 v12, vcc, v22, v9, v22
	v_fma_f32 v13, -v10, v11, 1.0
	v_fmac_f32_e32 v11, v13, v11
	v_mul_f32_e32 v13, v12, v11
	v_fma_f32 v14, -v10, v13, v12
	v_fmac_f32_e32 v13, v14, v11
	v_fma_f32 v10, -v10, v13, v12
	v_div_fmas_f32 v10, v10, v11, v13
	v_div_fixup_f32 v22, v10, v9, v22
	ds_write_b32 v7, v22 offset:49156
	s_waitcnt vmcnt(28)
	v_mul_f32_e32 v10, 0xbfb8aa3b, v23
	v_exp_f32_e32 v10, v10
	s_nop 0
	v_add_f32_e32 v9, 1.0, v10
	v_div_scale_f32 v10, s[12:13], v9, v9, v23
	v_rcp_f32_e32 v11, v10
	v_div_scale_f32 v12, vcc, v23, v9, v23
	v_fma_f32 v13, -v10, v11, 1.0
	v_fmac_f32_e32 v11, v13, v11
	v_mul_f32_e32 v13, v12, v11
	v_fma_f32 v14, -v10, v13, v12
	v_fmac_f32_e32 v13, v14, v11
	v_fma_f32 v10, -v10, v13, v12
	v_div_fmas_f32 v10, v10, v11, v13
	v_div_fixup_f32 v23, v10, v9, v23
	ds_write_b32 v8, v23 offset:4
	s_waitcnt vmcnt(27)
	v_mul_f32_e32 v10, 0xbfb8aa3b, v24
	v_exp_f32_e32 v10, v10
	s_nop 0
	v_add_f32_e32 v9, 1.0, v10
	v_div_scale_f32 v10, s[12:13], v9, v9, v24
	v_rcp_f32_e32 v11, v10
	v_div_scale_f32 v12, vcc, v24, v9, v24
	v_fma_f32 v13, -v10, v11, 1.0
	v_fmac_f32_e32 v11, v13, v11
	v_mul_f32_e32 v13, v12, v11
	v_fma_f32 v14, -v10, v13, v12
	v_fmac_f32_e32 v13, v14, v11
	v_fma_f32 v10, -v10, v13, v12
	v_div_fmas_f32 v10, v10, v11, v13
	v_div_fixup_f32 v24, v10, v9, v24
	ds_write_b32 v7, v24 offset:8
	s_waitcnt vmcnt(26)
	v_mul_f32_e32 v10, 0xbfb8aa3b, v25
	v_exp_f32_e32 v10, v10
	s_nop 0
	v_add_f32_e32 v9, 1.0, v10
	v_div_scale_f32 v10, s[12:13], v9, v9, v25
	v_rcp_f32_e32 v11, v10
	v_div_scale_f32 v12, vcc, v25, v9, v25
	v_fma_f32 v13, -v10, v11, 1.0
	v_fmac_f32_e32 v11, v13, v11
	v_mul_f32_e32 v13, v12, v11
	v_fma_f32 v14, -v10, v13, v12
	v_fmac_f32_e32 v13, v14, v11
	v_fma_f32 v10, -v10, v13, v12
	v_div_fmas_f32 v10, v10, v11, v13
	v_div_fixup_f32 v25, v10, v9, v25
	ds_write_b32 v7, v25 offset:24584
	s_waitcnt vmcnt(25)
	v_mul_f32_e32 v10, 0xbfb8aa3b, v26
	v_exp_f32_e32 v10, v10
	s_nop 0
	v_add_f32_e32 v9, 1.0, v10
	v_div_scale_f32 v10, s[12:13], v9, v9, v26
	v_rcp_f32_e32 v11, v10
	v_div_scale_f32 v12, vcc, v26, v9, v26
	v_fma_f32 v13, -v10, v11, 1.0
	v_fmac_f32_e32 v11, v13, v11
	v_mul_f32_e32 v13, v12, v11
	v_fma_f32 v14, -v10, v13, v12
	v_fmac_f32_e32 v13, v14, v11
	v_fma_f32 v10, -v10, v13, v12
	v_div_fmas_f32 v10, v10, v11, v13
	v_div_fixup_f32 v26, v10, v9, v26
	ds_write_b32 v7, v26 offset:49160
	s_waitcnt vmcnt(24)
	v_mul_f32_e32 v10, 0xbfb8aa3b, v27
	v_exp_f32_e32 v10, v10
	s_nop 0
	v_add_f32_e32 v9, 1.0, v10
	v_div_scale_f32 v10, s[12:13], v9, v9, v27
	v_rcp_f32_e32 v11, v10
	v_div_scale_f32 v12, vcc, v27, v9, v27
	v_fma_f32 v13, -v10, v11, 1.0
	v_fmac_f32_e32 v11, v13, v11
	v_mul_f32_e32 v13, v12, v11
	v_fma_f32 v14, -v10, v13, v12
	v_fmac_f32_e32 v13, v14, v11
	v_fma_f32 v10, -v10, v13, v12
	v_div_fmas_f32 v10, v10, v11, v13
	v_div_fixup_f32 v27, v10, v9, v27
	ds_write_b32 v8, v27 offset:8
	s_waitcnt vmcnt(23)
	v_mul_f32_e32 v10, 0xbfb8aa3b, v28
	v_exp_f32_e32 v10, v10
	s_nop 0
	v_add_f32_e32 v9, 1.0, v10
	v_div_scale_f32 v10, s[12:13], v9, v9, v28
	v_rcp_f32_e32 v11, v10
	v_div_scale_f32 v12, vcc, v28, v9, v28
	v_fma_f32 v13, -v10, v11, 1.0
	v_fmac_f32_e32 v11, v13, v11
	v_mul_f32_e32 v13, v12, v11
	v_fma_f32 v14, -v10, v13, v12
	v_fmac_f32_e32 v13, v14, v11
	v_fma_f32 v10, -v10, v13, v12
	v_div_fmas_f32 v10, v10, v11, v13
	v_div_fixup_f32 v28, v10, v9, v28
	ds_write_b32 v7, v28 offset:12
	s_waitcnt vmcnt(22)
	v_mul_f32_e32 v10, 0xbfb8aa3b, v29
	v_exp_f32_e32 v10, v10
	s_nop 0
	v_add_f32_e32 v9, 1.0, v10
	v_div_scale_f32 v10, s[12:13], v9, v9, v29
	v_rcp_f32_e32 v11, v10
	v_div_scale_f32 v12, vcc, v29, v9, v29
	v_fma_f32 v13, -v10, v11, 1.0
	v_fmac_f32_e32 v11, v13, v11
	v_mul_f32_e32 v13, v12, v11
	v_fma_f32 v14, -v10, v13, v12
	v_fmac_f32_e32 v13, v14, v11
	v_fma_f32 v10, -v10, v13, v12
	v_div_fmas_f32 v10, v10, v11, v13
	v_div_fixup_f32 v29, v10, v9, v29
	ds_write_b32 v7, v29 offset:24588
	s_waitcnt vmcnt(21)
	v_mul_f32_e32 v10, 0xbfb8aa3b, v30
	v_exp_f32_e32 v10, v10
	s_nop 0
	v_add_f32_e32 v9, 1.0, v10
	v_div_scale_f32 v10, s[12:13], v9, v9, v30
	v_rcp_f32_e32 v11, v10
	v_div_scale_f32 v12, vcc, v30, v9, v30
	v_fma_f32 v13, -v10, v11, 1.0
	v_fmac_f32_e32 v11, v13, v11
	v_mul_f32_e32 v13, v12, v11
	v_fma_f32 v14, -v10, v13, v12
	v_fmac_f32_e32 v13, v14, v11
	v_fma_f32 v10, -v10, v13, v12
	v_div_fmas_f32 v10, v10, v11, v13
	v_div_fixup_f32 v30, v10, v9, v30
	ds_write_b32 v7, v30 offset:49164
	s_waitcnt vmcnt(20)
	v_mul_f32_e32 v10, 0xbfb8aa3b, v31
	v_exp_f32_e32 v10, v10
	s_nop 0
	v_add_f32_e32 v9, 1.0, v10
	v_div_scale_f32 v10, s[12:13], v9, v9, v31
	v_rcp_f32_e32 v11, v10
	v_div_scale_f32 v12, vcc, v31, v9, v31
	v_fma_f32 v13, -v10, v11, 1.0
	v_fmac_f32_e32 v11, v13, v11
	v_mul_f32_e32 v13, v12, v11
	v_fma_f32 v14, -v10, v13, v12
	v_fmac_f32_e32 v13, v14, v11
	v_fma_f32 v10, -v10, v13, v12
	v_div_fmas_f32 v10, v10, v11, v13
	v_div_fixup_f32 v31, v10, v9, v31
	ds_write_b32 v8, v31 offset:12
	s_waitcnt vmcnt(19)
	v_mul_f32_e32 v10, 0xbfb8aa3b, v32
	v_exp_f32_e32 v10, v10
	s_nop 0
	v_add_f32_e32 v9, 1.0, v10
	v_div_scale_f32 v10, s[12:13], v9, v9, v32
	v_rcp_f32_e32 v11, v10
	v_div_scale_f32 v12, vcc, v32, v9, v32
	v_fma_f32 v13, -v10, v11, 1.0
	v_fmac_f32_e32 v11, v13, v11
	v_mul_f32_e32 v13, v12, v11
	v_fma_f32 v14, -v10, v13, v12
	v_fmac_f32_e32 v13, v14, v11
	v_fma_f32 v10, -v10, v13, v12
	v_div_fmas_f32 v10, v10, v11, v13
	v_div_fixup_f32 v32, v10, v9, v32
	ds_write_b32 v7, v32 offset:16
	s_waitcnt vmcnt(18)
; __device__ __forceinline__ void p0_modvec(const Params& p, LAS unsigned char* lds, int tid, int lane, int wave) {
;     ...
;     for (int i = tid; i < 9 * 2048; i += 512) { const float v = i < 8 * 2048 ? c[i] : cc[i - 8 * 2048]; svT[(i & 2047) * 12 + (i >> 11)] = v / (1.0f + __expf(-v)); }
	v_mul_f32_e32 v10, 0xbfb8aa3b, v33
	v_exp_f32_e32 v10, v10
	s_nop 0
	v_add_f32_e32 v9, 1.0, v10
	v_div_scale_f32 v10, s[12:13], v9, v9, v33
	v_rcp_f32_e32 v11, v10
	v_div_scale_f32 v12, vcc, v33, v9, v33
	v_fma_f32 v13, -v10, v11, 1.0
	v_fmac_f32_e32 v11, v13, v11
	v_mul_f32_e32 v13, v12, v11
	v_fma_f32 v14, -v10, v13, v12
	v_fmac_f32_e32 v13, v14, v11
	v_fma_f32 v10, -v10, v13, v12
	v_div_fmas_f32 v10, v10, v11, v13
	v_div_fixup_f32 v33, v10, v9, v33
	ds_write_b32 v7, v33 offset:24592
	s_waitcnt vmcnt(17)
	v_mul_f32_e32 v10, 0xbfb8aa3b, v34
	v_exp_f32_e32 v10, v10
	s_nop 0
	v_add_f32_e32 v9, 1.0, v10
	v_div_scale_f32 v10, s[12:13], v9, v9, v34
	v_rcp_f32_e32 v11, v10
	v_div_scale_f32 v12, vcc, v34, v9, v34
	v_fma_f32 v13, -v10, v11, 1.0
	v_fmac_f32_e32 v11, v13, v11
	v_mul_f32_e32 v13, v12, v11
	v_fma_f32 v14, -v10, v13, v12
	v_fmac_f32_e32 v13, v14, v11
	v_fma_f32 v10, -v10, v13, v12
	v_div_fmas_f32 v10, v10, v11, v13
	v_div_fixup_f32 v34, v10, v9, v34
	ds_write_b32 v7, v34 offset:49168
	s_waitcnt vmcnt(16)
	v_mul_f32_e32 v10, 0xbfb8aa3b, v35
	v_exp_f32_e32 v10, v10
	s_nop 0
	v_add_f32_e32 v9, 1.0, v10
	v_div_scale_f32 v10, s[12:13], v9, v9, v35
	v_rcp_f32_e32 v11, v10
	v_div_scale_f32 v12, vcc, v35, v9, v35
	v_fma_f32 v13, -v10, v11, 1.0
	v_fmac_f32_e32 v11, v13, v11
	v_mul_f32_e32 v13, v12, v11
	v_fma_f32 v14, -v10, v13, v12
	v_fmac_f32_e32 v13, v14, v11
	v_fma_f32 v10, -v10, v13, v12
	v_div_fmas_f32 v10, v10, v11, v13
	v_div_fixup_f32 v35, v10, v9, v35
	ds_write_b32 v8, v35 offset:16
	s_waitcnt vmcnt(15)
	v_mul_f32_e32 v10, 0xbfb8aa3b, v36
	v_exp_f32_e32 v10, v10
	s_nop 0
	v_add_f32_e32 v9, 1.0, v10
	v_div_scale_f32 v10, s[12:13], v9, v9, v36
	v_rcp_f32_e32 v11, v10
	v_div_scale_f32 v12, vcc, v36, v9, v36
	v_fma_f32 v13, -v10, v11, 1.0
	v_fmac_f32_e32 v11, v13, v11
	v_mul_f32_e32 v13, v12, v11
	v_fma_f32 v14, -v10, v13, v12
	v_fmac_f32_e32 v13, v14, v11
	v_fma_f32 v10, -v10, v13, v12
	v_div_fmas_f32 v10, v10, v11, v13
	v_div_fixup_f32 v36, v10, v9, v36
	ds_write_b32 v7, v36 offset:20
	s_waitcnt vmcnt(14)
	v_mul_f32_e32 v10, 0xbfb8aa3b, v37
	v_exp_f32_e32 v10, v10
	s_nop 0
	v_add_f32_e32 v9, 1.0, v10
	v_div_scale_f32 v10, s[12:13], v9, v9, v37
	v_rcp_f32_e32 v11, v10
	v_div_scale_f32 v12, vcc, v37, v9, v37
	v_fma_f32 v13, -v10, v11, 1.0
	v_fmac_f32_e32 v11, v13, v11
	v_mul_f32_e32 v13, v12, v11
	v_fma_f32 v14, -v10, v13, v12
	v_fmac_f32_e32 v13, v14, v11
	v_fma_f32 v10, -v10, v13, v12
	v_div_fmas_f32 v10, v10, v11, v13
	v_div_fixup_f32 v37, v10, v9, v37
	ds_write_b32 v7, v37 offset:24596
	s_waitcnt vmcnt(13)
	v_mul_f32_e32 v10, 0xbfb8aa3b, v38
	v_exp_f32_e32 v10, v10
	s_nop 0
	v_add_f32_e32 v9, 1.0, v10
	v_div_scale_f32 v10, s[12:13], v9, v9, v38
	v_rcp_f32_e32 v11, v10
	v_div_scale_f32 v12, vcc, v38, v9, v38
	v_fma_f32 v13, -v10, v11, 1.0
	v_fmac_f32_e32 v11, v13, v11
	v_mul_f32_e32 v13, v12, v11
	v_fma_f32 v14, -v10, v13, v12
	v_fmac_f32_e32 v13, v14, v11
	v_fma_f32 v10, -v10, v13, v12
	v_div_fmas_f32 v10, v10, v11, v13
	v_div_fixup_f32 v38, v10, v9, v38
	ds_write_b32 v7, v38 offset:49172
	s_waitcnt vmcnt(12)
	v_mul_f32_e32 v10, 0xbfb8aa3b, v39
	v_exp_f32_e32 v10, v10
	s_nop 0
	v_add_f32_e32 v9, 1.0, v10
	v_div_scale_f32 v10, s[12:13], v9, v9, v39
	v_rcp_f32_e32 v11, v10
	v_div_scale_f32 v12, vcc, v39, v9, v39
	v_fma_f32 v13, -v10, v11, 1.0
	v_fmac_f32_e32 v11, v13, v11
	v_mul_f32_e32 v13, v12, v11
	v_fma_f32 v14, -v10, v13, v12
	v_fmac_f32_e32 v13, v14, v11
	v_fma_f32 v10, -v10, v13, v12
	v_div_fmas_f32 v10, v10, v11, v13
	v_div_fixup_f32 v39, v10, v9, v39
	ds_write_b32 v8, v39 offset:20
	s_waitcnt vmcnt(11)
	v_mul_f32_e32 v10, 0xbfb8aa3b, v40
	v_exp_f32_e32 v10, v10
	s_nop 0
	v_add_f32_e32 v9, 1.0, v10
	v_div_scale_f32 v10, s[12:13], v9, v9, v40
	v_rcp_f32_e32 v11, v10
	v_div_scale_f32 v12, vcc, v40, v9, v40
	v_fma_f32 v13, -v10, v11, 1.0
	v_fmac_f32_e32 v11, v13, v11
	v_mul_f32_e32 v13, v12, v11
	v_fma_f32 v14, -v10, v13, v12
	v_fmac_f32_e32 v13, v14, v11
	v_fma_f32 v10, -v10, v13, v12
	v_div_fmas_f32 v10, v10, v11, v13
	v_div_fixup_f32 v40, v10, v9, v40
	ds_write_b32 v7, v40 offset:24
	s_waitcnt vmcnt(10)
	v_mul_f32_e32 v10, 0xbfb8aa3b, v41
	v_exp_f32_e32 v10, v10
	s_nop 0
	v_add_f32_e32 v9, 1.0, v10
	v_div_scale_f32 v10, s[12:13], v9, v9, v41
	v_rcp_f32_e32 v11, v10
	v_div_scale_f32 v12, vcc, v41, v9, v41
	v_fma_f32 v13, -v10, v11, 1.0
	v_fmac_f32_e32 v11, v13, v11
	v_mul_f32_e32 v13, v12, v11
	v_fma_f32 v14, -v10, v13, v12
	v_fmac_f32_e32 v13, v14, v11
	v_fma_f32 v10, -v10, v13, v12
	v_div_fmas_f32 v10, v10, v11, v13
	v_div_fixup_f32 v41, v10, v9, v41
	ds_write_b32 v7, v41 offset:24600
	s_waitcnt vmcnt(9)
	v_mul_f32_e32 v10, 0xbfb8aa3b, v42
	v_exp_f32_e32 v10, v10
	s_nop 0
	v_add_f32_e32 v9, 1.0, v10
	v_div_scale_f32 v10, s[12:13], v9, v9, v42
	v_rcp_f32_e32 v11, v10
	v_div_scale_f32 v12, vcc, v42, v9, v42
	v_fma_f32 v13, -v10, v11, 1.0
	v_fmac_f32_e32 v11, v13, v11
	v_mul_f32_e32 v13, v12, v11
	v_fma_f32 v14, -v10, v13, v12
	v_fmac_f32_e32 v13, v14, v11
	v_fma_f32 v10, -v10, v13, v12
	v_div_fmas_f32 v10, v10, v11, v13
	v_div_fixup_f32 v42, v10, v9, v42
	ds_write_b32 v7, v42 offset:49176
	s_waitcnt vmcnt(8)
	v_mul_f32_e32 v10, 0xbfb8aa3b, v43
	v_exp_f32_e32 v10, v10
	s_nop 0
	v_add_f32_e32 v9, 1.0, v10
	v_div_scale_f32 v10, s[12:13], v9, v9, v43
	v_rcp_f32_e32 v11, v10
	v_div_scale_f32 v12, vcc, v43, v9, v43
	v_fma_f32 v13, -v10, v11, 1.0
	v_fmac_f32_e32 v11, v13, v11
	v_mul_f32_e32 v13, v12, v11
	v_fma_f32 v14, -v10, v13, v12
	v_fmac_f32_e32 v13, v14, v11
	v_fma_f32 v10, -v10, v13, v12
	v_div_fmas_f32 v10, v10, v11, v13
	v_div_fixup_f32 v43, v10, v9, v43
	ds_write_b32 v8, v43 offset:24
	s_waitcnt vmcnt(7)
; #define GAS __attribute__((address_space(1)))
; #define LAS __attribute__((address_space(3)))
; __device__ __forceinline__ void p0_modvec(const Params& p, LAS unsigned char* lds, int tid, int lane, int wave) {
;     ...
;     for (int i = tid; i < 9 * 2048; i += 512) { const float v = i < 8 * 2048 ? c[i] : cc[i - 8 * 2048]; svT[(i & 2047) * 12 + (i >> 11)] = v / (1.0f + __expf(-v)); }
;     float* MOD = (float*)(p.ws + WS_MOD);
;     const int ln = lane & 15, lk = lane >> 4;
;     const LAS float* svw = svT + (wave * 256 + lk) * 12 + min(ln, 11);
;     for (int u = blockIdx.x; u < 2 * (DMODW / UC); u += gridDim.x) {
;         __syncthreads();
;         const int l = u / (DMODW / UC), col0 = (u % (DMODW / UC)) * UC;
;         const GAS float* Wu = (const GAS float*)uniform_ptr(p.in[IN_WMOD] + (size_t)l * D * DMODW + col0 + (size_t)(wave * 256) * DMODW);
;         const unsigned loff = (unsigned)(lk * DMODW + ln);
	v_mul_f32_e32 v10, 0xbfb8aa3b, v44
	v_exp_f32_e32 v10, v10
	s_nop 0
	v_add_f32_e32 v9, 1.0, v10
	v_div_scale_f32 v10, s[12:13], v9, v9, v44
	v_rcp_f32_e32 v11, v10
	v_div_scale_f32 v12, vcc, v44, v9, v44
	v_fma_f32 v13, -v10, v11, 1.0
	v_fmac_f32_e32 v11, v13, v11
	v_mul_f32_e32 v13, v12, v11
	v_fma_f32 v14, -v10, v13, v12
	v_fmac_f32_e32 v13, v14, v11
	v_fma_f32 v10, -v10, v13, v12
	v_div_fmas_f32 v10, v10, v11, v13
	v_div_fixup_f32 v44, v10, v9, v44
	ds_write_b32 v7, v44 offset:28
	s_waitcnt vmcnt(6)
	v_mul_f32_e32 v10, 0xbfb8aa3b, v45
	v_exp_f32_e32 v10, v10
	s_nop 0
	v_add_f32_e32 v9, 1.0, v10
	v_div_scale_f32 v10, s[12:13], v9, v9, v45
	v_rcp_f32_e32 v11, v10
	v_div_scale_f32 v12, vcc, v45, v9, v45
	v_fma_f32 v13, -v10, v11, 1.0
	v_fmac_f32_e32 v11, v13, v11
	v_mul_f32_e32 v13, v12, v11
	v_fma_f32 v14, -v10, v13, v12
	v_fmac_f32_e32 v13, v14, v11
	v_fma_f32 v10, -v10, v13, v12
	v_div_fmas_f32 v10, v10, v11, v13
	v_div_fixup_f32 v45, v10, v9, v45
	ds_write_b32 v7, v45 offset:24604
	s_waitcnt vmcnt(5)
	v_mul_f32_e32 v10, 0xbfb8aa3b, v46
	v_exp_f32_e32 v10, v10
	s_nop 0
	v_add_f32_e32 v9, 1.0, v10
	v_div_scale_f32 v10, s[12:13], v9, v9, v46
	v_rcp_f32_e32 v11, v10
	v_div_scale_f32 v12, vcc, v46, v9, v46
	v_fma_f32 v13, -v10, v11, 1.0
	v_fmac_f32_e32 v11, v13, v11
	v_mul_f32_e32 v13, v12, v11
	v_fma_f32 v14, -v10, v13, v12
	v_fmac_f32_e32 v13, v14, v11
	v_fma_f32 v10, -v10, v13, v12
	v_div_fmas_f32 v10, v10, v11, v13
	v_div_fixup_f32 v46, v10, v9, v46
	ds_write_b32 v7, v46 offset:49180
	s_waitcnt vmcnt(4)
	v_mul_f32_e32 v10, 0xbfb8aa3b, v47
	v_exp_f32_e32 v10, v10
	s_nop 0
	v_add_f32_e32 v9, 1.0, v10
	v_div_scale_f32 v10, s[12:13], v9, v9, v47
	v_rcp_f32_e32 v11, v10
	v_div_scale_f32 v12, vcc, v47, v9, v47
	v_fma_f32 v13, -v10, v11, 1.0
	v_fmac_f32_e32 v11, v13, v11
	v_mul_f32_e32 v13, v12, v11
	v_fma_f32 v14, -v10, v13, v12
	v_fmac_f32_e32 v13, v14, v11
	v_fma_f32 v10, -v10, v13, v12
	v_div_fmas_f32 v10, v10, v11, v13
	v_div_fixup_f32 v47, v10, v9, v47
	ds_write_b32 v8, v47 offset:28
	s_waitcnt vmcnt(3)
	v_mul_f32_e32 v10, 0xbfb8aa3b, v48
	v_exp_f32_e32 v10, v10
	s_nop 0
	v_add_f32_e32 v9, 1.0, v10
	v_div_scale_f32 v10, s[12:13], v9, v9, v48
	v_rcp_f32_e32 v11, v10
	v_div_scale_f32 v12, vcc, v48, v9, v48
	v_fma_f32 v13, -v10, v11, 1.0
	v_fmac_f32_e32 v11, v13, v11
	v_mul_f32_e32 v13, v12, v11
	v_fma_f32 v14, -v10, v13, v12
	v_fmac_f32_e32 v13, v14, v11
	v_fma_f32 v10, -v10, v13, v12
	v_div_fmas_f32 v10, v10, v11, v13
	v_div_fixup_f32 v48, v10, v9, v48
	ds_write_b32 v7, v48 offset:32
	s_waitcnt vmcnt(2)
	v_mul_f32_e32 v10, 0xbfb8aa3b, v49
	v_exp_f32_e32 v10, v10
	s_nop 0
	v_add_f32_e32 v9, 1.0, v10
	v_div_scale_f32 v10, s[12:13], v9, v9, v49
	v_rcp_f32_e32 v11, v10
	v_div_scale_f32 v12, vcc, v49, v9, v49
	v_fma_f32 v13, -v10, v11, 1.0
	v_fmac_f32_e32 v11, v13, v11
	v_mul_f32_e32 v13, v12, v11
	v_fma_f32 v14, -v10, v13, v12
	v_fmac_f32_e32 v13, v14, v11
	v_fma_f32 v10, -v10, v13, v12
	v_div_fmas_f32 v10, v10, v11, v13
	v_div_fixup_f32 v49, v10, v9, v49
	ds_write_b32 v7, v49 offset:24608
	s_waitcnt vmcnt(1)
	v_mul_f32_e32 v10, 0xbfb8aa3b, v50
	v_exp_f32_e32 v10, v10
	s_nop 0
	v_add_f32_e32 v9, 1.0, v10
	v_div_scale_f32 v10, s[12:13], v9, v9, v50
	v_rcp_f32_e32 v11, v10
	v_div_scale_f32 v12, vcc, v50, v9, v50
	v_fma_f32 v13, -v10, v11, 1.0
	v_fmac_f32_e32 v11, v13, v11
	v_mul_f32_e32 v13, v12, v11
	v_fma_f32 v14, -v10, v13, v12
	v_fmac_f32_e32 v13, v14, v11
	v_fma_f32 v10, -v10, v13, v12
	v_div_fmas_f32 v10, v10, v11, v13
	v_div_fixup_f32 v50, v10, v9, v50
	ds_write_b32 v7, v50 offset:49184
	s_waitcnt vmcnt(0)
	v_mul_f32_e32 v10, 0xbfb8aa3b, v51
	v_exp_f32_e32 v10, v10
	s_nop 0
	v_add_f32_e32 v9, 1.0, v10
	v_div_scale_f32 v10, s[12:13], v9, v9, v51
	v_rcp_f32_e32 v11, v10
	v_div_scale_f32 v12, vcc, v51, v9, v51
	v_fma_f32 v13, -v10, v11, 1.0
	v_fmac_f32_e32 v11, v13, v11
	v_mul_f32_e32 v13, v12, v11
	v_fma_f32 v14, -v10, v13, v12
	v_fmac_f32_e32 v13, v14, v11
	v_fma_f32 v10, -v10, v13, v12
	v_div_fmas_f32 v10, v10, v11, v13
	v_div_fixup_f32 v51, v10, v9, v51
	ds_write_b32 v8, v51 offset:32
	s_nop 0
	s_nop 0
	s_nop 0
	s_nop 0
	s_nop 0
	s_nop 0
	s_nop 0
	s_nop 0
	s_nop 0
	s_nop 0
	s_nop 0
	s_nop 0
	s_nop 0
	s_nop 0
	s_nop 0
	s_or_b64 exec, exec, s[2:3]
	s_cmpk_gt_i32 s86, 0xff
	s_cbranch_scc1 .LBB0_91
	s_add_u32 s33, s88, 0x100000
	s_addc_u32 s62, s89, 0
	v_and_b32_e32 v3, 15, v0
	v_lshrrev_b32_e32 v4, 4, v1
	s_lshl_b32 s2, s10, 8
	v_or_b32_e32 v2, s2, v4
	v_min_u32_e32 v5, 11, v3
	v_mul_lo_u32 v2, v2, 48
	v_lshlrev_b32_e32 v5, 2, v5
	v_add3_u32 v40, 0, v2, v5
	s_mul_hi_u32 s65, s2, 0x12000
	v_lshlrev_b32_e32 v5, 2, v4
	s_mul_i32 s2, s10, 9
	v_mul_u32_u24_e32 v2, 0x4800, v4
	v_cmp_ne_u32_e32 vcc, 3, v4
	v_add_u32_e32 v4, s2, v5
	v_or_b32_e32 v6, 1, v5
	v_or_b32_e32 v7, 2, v5
	v_or_b32_e32 v5, 3, v5
	s_mul_i32 s63, s10, 0x1200000
	s_add_i32 s66, 0, 0x18000
	s_movk_i32 s3, 0x240
	v_cmp_gt_u32_e64 s[10:11], 9, v6
	v_add_u32_e32 v6, s2, v6
	v_cmp_gt_u32_e64 s[6:7], 9, v7
	v_add_u32_e32 v7, s2, v7
	v_cmp_gt_u32_e64 s[8:9], 9, v5
	v_add_u32_e32 v5, s2, v5
	v_or_b32_e32 v2, v2, v3
	v_lshl_add_u32 v3, v3, 2, s66
	v_mul_lo_u32 v4, v4, s3
	v_mul_lo_u32 v6, v6, s3
	v_mul_lo_u32 v7, v7, s3
	v_mul_lo_u32 v5, v5, s3
	s_mov_b32 s64, 0x12000
	v_mov_b32_e32 v39, 0
	v_lshlrev_b32_e32 v38, 2, v2
	v_add_u32_e32 v41, 0x400, v40
	v_add_u32_e32 v42, 0x600, v40
	v_add_u32_e32 v43, 0x800, v40
	v_add_u32_e32 v44, 0xc00, v40
	v_add_u32_e32 v45, 0x1000, v40
	v_add_u32_e32 v46, 0x1200, v40
	v_add_u32_e32 v47, 0x1400, v40
	v_add_u32_e32 v48, 0x1800, v40
	v_add_u32_e32 v49, 0x1c00, v40
	v_add_u32_e32 v50, 0x1e00, v40
	v_add_u32_e32 v51, 0x2000, v40
	v_add_u32_e32 v52, 0x2400, v40
	v_add_u32_e32 v53, 0x2800, v40
	v_add_u32_e32 v54, 0x2a00, v40
	v_add_u32_e32 v55, 0x2c00, v40
	v_add_u32_e32 v56, v3, v4
	v_add_u32_e32 v57, v3, v6
	v_add_u32_e32 v58, v3, v7
	v_add_u32_e32 v59, v3, v5
	s_mov_b32 s67, s86
	s_mov_b64 s[2:3], 0xca8000
	s_mov_b64 s[14:15], 0xcf0000
	s_mov_b64 s[16:17], 0xd38000
	s_mov_b64 s[18:19], 0xd80000
	s_mov_b64 s[20:21], 0xdc8000
	s_mov_b64 s[22:23], 0xe10000
	s_mov_b64 s[24:25], 0xe58000
	s_mov_b64 s[26:27], 0xea0000
	s_mov_b64 s[28:29], 0xee8000
	s_mov_b64 s[30:31], 0xf30000
	s_mov_b64 s[34:35], 0xf78000
	s_mov_b64 s[36:37], 0xfc0000
	s_mov_b64 s[38:39], 0x1008000
	s_mov_b64 s[40:41], 0x1050000
	s_mov_b64 s[42:43], 0x1098000
	s_mov_b64 s[44:45], 0x10e0000
	s_mov_b64 s[46:47], 0x1128000
	s_mov_b64 s[48:49], 0x1170000
	s_mov_b64 s[50:51], 0x11b8000
	s_branch .LBB0_16
